# younger-half priority raise also at kernel entry (covers the prep phase) in addition to the GLA-entry raise
# speedup vs baseline: 1.0017x; 1.0017x over previous
; #define LAS __attribute__((address_space(3)))
; __global__ void __launch_bounds__(512, 2) mega(const Params p_arg) {
;     extern __shared__ __attribute__((aligned(16))) unsigned char shm[];
;     LAS unsigned char* lds = (LAS unsigned char*)shm;
;     typedef const Params __attribute__((address_space(4))) * KArgPtr;
;     const int phase_lo = p_arg.phase_lo, phase_hi = p_arg.phase_hi;
;     pg8::StaticOrder S;
;     unsigned bar_k = 0;
;     for (int ph = phase_lo; ph < phase_hi; ++ph) {
;         KArgPtr kp = (KArgPtr)__builtin_amdgcn_kernarg_segment_ptr(); asm volatile("" : "+s"(kp));
;         const Params& p = *(const Params*)kp;
;         bf16_t* xb = (bf16_t*)(p.ws + OFF_XB); bf16_t* proj = (bf16_t*)(p.ws + OFF_PROJ); float* ssq = (float*)(p.ws + OFF_SSQ);
.LBB0_1:
	s_mov_b64 s[62:63], s[0:1]
	s_cmpk_gt_i32 s65, 0x3e8
	s_mov_b32 s60, s2
	s_cselect_b64 s[0:1], -1, 0
	s_add_u32 s66, s62, 0x98
	s_addc_u32 s67, s63, 0
	s_lshl_b32 s3, s60, 3
	v_cndmask_b32_e64 v3, 0, 1, s[0:1]
	v_writelane_b32 v254, s3, 0
	s_lshl_b32 s3, s60, 7
	v_writelane_b32 v254, s3, 1
	s_add_i32 s0, 0, 0x20800
	v_writelane_b32 v254, s0, 2
	s_add_i32 s0, 0, 0x20900
	v_writelane_b32 v254, s0, 3
	s_add_i32 s0, 0, 0x20a00
	v_writelane_b32 v254, s0, 4
	s_add_i32 s0, 0, 0x20b00
	v_writelane_b32 v254, s0, 5
	s_add_i32 s0, 0, 0x21000
	v_writelane_b32 v254, s0, 6
	s_add_i32 s0, 0, 0x21100
	v_writelane_b32 v254, s0, 7
	s_add_i32 s0, 0, 0x21200
	v_and_b32_e32 v1, 0x3fffffff, v0
	v_writelane_b32 v254, s0, 8
	s_add_i32 s0, 0, 0x21300
	v_writelane_b32 v254, s0, 9
	v_cmp_eq_u32_e64 s[0:1], 0, v1
	v_and_b32_e32 v144, 0x3ff, v0
	s_movk_i32 s2, 0x100
	v_writelane_b32 v254, s0, 10
	v_lshlrev_b32_e32 v0, 4, v144
	v_lshlrev_b32_e32 v2, 2, v144
	v_writelane_b32 v254, s1, 11
	v_cmp_eq_u32_e64 s[0:1], 0, v144
	v_add_u32_e32 v0, 0, v0
	v_add_u32_e32 v221, 0x20800, v0
	v_writelane_b32 v254, s0, 12
	v_add_u32_e32 v0, 0, v2
	v_add_u32_e32 v222, 0x21800, v0
	v_writelane_b32 v254, s1, 13
	v_cmp_gt_u32_e64 s[0:1], s2, v144
	v_mbcnt_lo_u32_b32 v0, -1, 0
	s_mov_b32 s6, s64
	v_writelane_b32 v254, s0, 14
	v_mov_b32_e32 v147, 0
	v_mov_b32_e32 v145, 0x1e842000
	v_writelane_b32 v254, s1, 15
	v_cmp_ne_u32_e64 s[0:1], 1, v3
	s_mov_b32 s35, 0x8000
	v_mov_b32_e32 v220, 0x358637bd
	v_writelane_b32 v254, s0, 16
	s_mov_b32 s33, 0x800000
	s_movk_i32 s36, 0x7fff
	v_writelane_b32 v254, s1, 17
	v_writelane_b32 v254, s60, 18
	v_writelane_b32 v254, s62, 19
	s_mov_b32 s79, 0xbfb8aa3b
	s_movk_i32 s80, 0x1c00
	v_writelane_b32 v254, s63, 20
	v_writelane_b32 v254, s64, 21
	s_mov_b32 s81, 0x3f317217
	s_mov_b32 s90, 0x7f800000
	v_mbcnt_hi_u32_b32 v223, -1, v0
	v_mov_b32_e32 v224, 1
	v_mov_b64_e32 v[148:149], 0x200
	v_mov_b64_e32 v[150:151], 0x1ff
	v_mov_b32_e32 v225, 0x41b17218
	v_mov_b32_e32 v226, 0x1c00
	v_mov_b64_e32 v[248:249], 0x780
	v_mov_b64_e32 v[154:155], 0x77f
	s_mov_b32 s30, 0
	s_mov_b32 s69, 0
	s_mov_b32 s78, 0x3db504f3
	v_writelane_b32 v254, s65, 22
	v_readfirstlane_b32 s4, v144
	s_lshr_b32 s4, s4, 8
	s_cmp_eq_u32 s4, 0
	s_cbranch_scc1 .Lk_prio_done
	s_setprio 1
.Lk_prio_done:
	s_branch .LBB0_4
.LBB0_2:
	s_or_b64 exec, exec, s[0:1]
	s_mov_b32 s30, s70
